# attn-B tile loop: redundant lgkmcnt(0) before the post-M barrier removed (on top of v70)
# speedup vs baseline: 1.0006x; 1.0006x over previous
.LBB0_698:
	s_add_i32 s12, s29, 0xffff8000
	s_add_i32 s16, s29, 0x4000
	s_and_b32 s13, s16, 0xc000
	s_and_b32 s12, s12, 0xc000
	v_add_u32_e32 v2, s12, v172
	ds_read_b128 v[186:189], v2 offset:0
	ds_read_b128 v[190:193], v2 offset:0x2000
	v_add_u32_e32 v2, s12, v173
	ds_read_b128 v[194:197], v2 offset:0
	ds_read_b128 v[198:201], v2 offset:0x2000
	v_add_u32_e32 v2, s12, v184
	ds_read_b128 v[202:205], v2 offset:0
	ds_read_b128 v[206:209], v2 offset:0x2000
	v_add_u32_e32 v2, s12, v185
	ds_read_b128 v[210:213], v2 offset:0
	ds_read_b128 v[214:217], v2 offset:0x2000
	v_add_u32_e32 v149, s13, v171
	ds_read_b64_tr_b16 v[218:219], v149 offset:0
	ds_read_b64_tr_b16 v[220:221], v149 offset:0x800
	ds_read_b64_tr_b16 v[222:223], v149 offset:0x1000
	ds_read_b64_tr_b16 v[224:225], v149 offset:0x1800
	ds_read_b64_tr_b16 v[226:227], v149 offset:0x2000
	ds_read_b64_tr_b16 v[228:229], v149 offset:0x2800
	ds_read_b64_tr_b16 v[242:243], v149 offset:0x3000
	ds_read_b64_tr_b16 v[244:245], v149 offset:0x3800
	s_cmp_gt_i32 s27, s19
	s_cselect_b64 vcc, -1, 0
	s_and_b64 s[12:13], vcc, exec
	s_cselect_b32 s12, 0x8000, 0
	v_xor_b32_e32 v2, s12, v164
	v_mov_b32_e32 v4, v3
	v_mov_b32_e32 v5, v3
	s_waitcnt lgkmcnt(8)
	s_nop 1
	v_mfma_f32_32x32x16_bf16 v[70:85], v[118:121], v[2:5], 0
	v_mfma_f32_32x32x16_bf16 v[86:101], v[186:189], v[102:105], v[70:85]
	v_mfma_f32_32x32x16_bf16 v[70:85], v[190:193], v[102:105], v[70:85]
	v_mfma_f32_32x32x16_bf16 v[86:101], v[194:197], v[106:109], v[86:101]
	v_mfma_f32_32x32x16_bf16 v[70:85], v[198:201], v[106:109], v[70:85]
	v_mfma_f32_32x32x16_bf16 v[86:101], v[202:205], v[110:113], v[86:101]
	v_mfma_f32_32x32x16_bf16 v[70:85], v[206:209], v[110:113], v[70:85]
	v_mfma_f32_32x32x16_bf16 v[86:101], v[210:213], v[114:117], v[86:101]
	v_mfma_f32_32x32x16_bf16 v[70:85], v[214:217], v[114:117], v[70:85]
	ds_read_b64_tr_b16 v[186:187], v149 offset:0x200
	ds_read_b64_tr_b16 v[188:189], v149 offset:0xa00
	ds_read_b64_tr_b16 v[190:191], v149 offset:0x1200
	ds_read_b64_tr_b16 v[192:193], v149 offset:0x1a00
	ds_read_b64_tr_b16 v[194:195], v149 offset:0x2200
	ds_read_b64_tr_b16 v[196:197], v149 offset:0x2a00
	ds_read_b64_tr_b16 v[198:199], v149 offset:0x3200
	ds_read_b64_tr_b16 v[200:201], v149 offset:0x3a00
	s_waitcnt lgkmcnt(8)
	v_mfma_f32_32x32x16_bf16 v[54:69], v[134:137], v[218:221], v[54:69]
	v_mfma_f32_32x32x16_bf16 v[54:69], v[130:133], v[222:225], v[54:69]
	v_mfma_f32_32x32x16_bf16 v[54:69], v[126:129], v[226:229], v[54:69]
	v_mfma_f32_32x32x16_bf16 v[54:69], v[122:125], v[242:245], v[54:69]
	ds_read_b64_tr_b16 v[202:203], v149 offset:0x400
	ds_read_b64_tr_b16 v[204:205], v149 offset:0xc00
	ds_read_b64_tr_b16 v[206:207], v149 offset:0x1400
	ds_read_b64_tr_b16 v[208:209], v149 offset:0x1c00
	ds_read_b64_tr_b16 v[210:211], v149 offset:0x2400
	ds_read_b64_tr_b16 v[212:213], v149 offset:0x2c00
	ds_read_b64_tr_b16 v[214:215], v149 offset:0x3400
	ds_read_b64_tr_b16 v[216:217], v149 offset:0x3c00
	s_waitcnt lgkmcnt(8)
	v_mfma_f32_32x32x16_bf16 v[38:53], v[134:137], v[186:189], v[38:53]
	v_mfma_f32_32x32x16_bf16 v[38:53], v[130:133], v[190:193], v[38:53]
	v_mfma_f32_32x32x16_bf16 v[38:53], v[126:129], v[194:197], v[38:53]
	v_mfma_f32_32x32x16_bf16 v[38:53], v[122:125], v[198:201], v[38:53]
	ds_read_b64_tr_b16 v[186:187], v149 offset:0x600
	ds_read_b64_tr_b16 v[188:189], v149 offset:0xe00
	ds_read_b64_tr_b16 v[190:191], v149 offset:0x1600
	ds_read_b64_tr_b16 v[192:193], v149 offset:0x1e00
	ds_read_b64_tr_b16 v[194:195], v149 offset:0x2600
	ds_read_b64_tr_b16 v[196:197], v149 offset:0x2e00
	ds_read_b64_tr_b16 v[198:199], v149 offset:0x3600
	ds_read_b64_tr_b16 v[200:201], v149 offset:0x3e00
	s_waitcnt lgkmcnt(8)
	v_mfma_f32_32x32x16_bf16 v[22:37], v[134:137], v[202:205], v[22:37]
	v_mfma_f32_32x32x16_bf16 v[22:37], v[130:133], v[206:209], v[22:37]
	v_mfma_f32_32x32x16_bf16 v[22:37], v[126:129], v[210:213], v[22:37]
	v_mfma_f32_32x32x16_bf16 v[22:37], v[122:125], v[214:217], v[22:37]
	s_waitcnt lgkmcnt(0)
	v_mfma_f32_32x32x16_bf16 v[6:21], v[134:137], v[186:189], v[6:21]
	v_mfma_f32_32x32x16_bf16 v[6:21], v[130:133], v[190:193], v[6:21]
	v_mfma_f32_32x32x16_bf16 v[6:21], v[126:129], v[194:197], v[6:21]
	v_mfma_f32_32x32x16_bf16 v[6:21], v[122:125], v[198:201], v[6:21]

	s_barrier
	s_add_i32 s12, s28, 0xffffff80
	v_cvt_f32_u32_e32 v2, s12
	s_cmp_lg_u32 s19, s27
	v_sub_f32_e32 v4, v163, v2
	s_cbranch_scc0 .Lb_diag
